# E1/E2: for row blocks with at most 64 valid rows the two waves owning rows 64..127 skip their fragment reads and MFMAs (results of those rows are never stored)
# speedup vs baseline: 1.0252x; 1.0024x over previous
; template <bool ABF, bool BBF, class RowF, class ColF, class Epi>
; __device__ __forceinline__ void gemm_tile(char* smem, int K, RowF rowptr, ColF colptr, int ldb, Epi epi) {
;     ...
; #pragma unroll
;   for (int i = 0; i < 4; i++)
; #pragma unroll
;     for (int j = 0; j < 4; j++) acc[i][j] = f32x4{0.f, 0.f, 0.f, 0.f};
;   constexpr int NA = ABF ? 4 : 8;
;   const int ar0 = ABF ? (tid >> 3) : (tid >> 4);
;   const int ac = ABF ? (tid & 7) * 8 : (tid & 15) * 4;
;   constexpr int ARS = ABF ? 32 : 16;
;   const char* ap[NA];
; #pragma unroll
;   for (int i = 0; i < NA; i++) ap[i] = (const char*)rowptr(ar0 + ARS * i) + ac * (ABF ? 2 : 4);
;   const int bc = tid & 127, kh = tid >> 7;
;   const float* bp = BBF ? nullptr : ((const float*)colptr(bc) + (size_t)(kh * 32) * ldb);
;   const int br0 = tid >> 3, bcc = (tid & 7) * 8;
;   const char* bq[4];
;   if (BBF) {
; #pragma unroll
;     for (int i = 0; i < 4; i++) bq[i] = (const char*)colptr(br0 + 32 * i) + bcc * 2;
;   }
;   u32x4 ra[NA];
;   float rb[BBF ? 1 : 32];
;   u32x4 rbb[BBF ? 4 : 1];
;   auto gload = [&](int k0) {
; #pragma unroll
;     for (int i = 0; i < NA; i++) ra[i] = *(const u32x4*)(ap[i] + (size_t)k0 * (ABF ? 2 : 4));
;     if (BBF) {
; #pragma unroll
;       for (int i = 0; i < 4; i++) rbb[BBF ? i : 0] = *(const u32x4*)(bq[i] + (size_t)k0 * 2);
;     } else {
;       const float* b = bp + (size_t)k0 * ldb;
; #pragma unroll
;       for (int j = 0; j < 32; j++) rb[BBF ? 0 : j] = b[(size_t)j * ldb];
;     }
;   };
; __device__ void phaseE1(const Params& p, char* smem) {
;     ...
;     const int rbg = q, jt = j;
;     int e = 0;
;     while (s_rb[e + 1] <= rbg) e++;
;     const int rb = rbg - s_rb[e];
;     const int cnt = p.cnt[e];
;     const int rows = min(128, cnt - rb * 128);
;     const int* lt = p.list_tok + e * CAP + rb * 128;
;     const int slot0 = s_off[e] + rb * 128;
;     const int j0 = jt * 64;
;     const u16* wg = p.WgT + (size_t)e * DEXP * DM;
;     const u16* wu = p.WuT + (size_t)e * DEXP * DM;
;     auto rowf = [&](int r) { int rr = r < rows ? r : 0; return (const void*)(p.X1B + (size_t)lt[rr] * DM); };
;     auto colf = [&](int c) { return (const void*)(((c & 32) ? wu : wg) + (size_t)(j0 + (c >> 6) * 32 + (c & 31)) * DM); };
.LBB0_1273:
	s_or_b64 exec, exec, s[16:17]
	s_cmp_lg_u32 s33, -1
	s_cselect_b32 s2, s33, 0
	s_cselect_b32 s16, s1, 0
	v_mov_b32_e32 v0, s2
	v_mov_b32_e32 v1, s16
	s_waitcnt lgkmcnt(0)
	s_barrier
	flat_load_dword v0, v[0:1] sc0 sc1
	s_waitcnt vmcnt(0)
	s_mov_b64 s[18:19], -1
	s_waitcnt lgkmcnt(0)
	v_cmp_lt_i32_e32 vcc, v0, v153
	s_and_saveexec_b64 s[16:17], vcc
	s_cbranch_execz .LBB0_1268
	v_lshrrev_b32_e32 v90, 4, v128
	v_xor_b32_e32 v90, v90, v128
	v_and_b32_e32 v90, 7, v90
	v_lshlrev_b32_e32 v92, 4, v90
	v_mov_b32_e32 v93, 0
	v_sub_u32_e32 v94, v92, v124
	v_lshrrev_b32_e32 v90, 6, v128
	v_ashrrev_i32_e32 v95, 31, v94
	v_readfirstlane_b32 s100, v90
	s_lshl_b32 s100, s100, 10
	s_mov_b64 s[18:19], 0
	v_mbcnt_lo_u32_b32 v1, -1, 0
	v_mbcnt_hi_u32_b32 v1, -1, v1
	v_lshl_add_u32 v1, v1, 2, s25
	ds_read_b32 v1, v1
	s_waitcnt lgkmcnt(0)
	v_cmp_le_i32_e32 vcc, v1, v0
	s_bcnt1_i32_b64 s2, vcc
	v_mov_b32_e32 v96, s2
	s_or_b64 exec, exec, s[18:19]
	v_lshl_add_u32 v6, v96, 2, 0
	v_add_u32_e32 v6, 0x10000, v6
	ds_read2_b32 v[6:7], v6 offset1:1
	v_lshl_add_u32 v10, v96, 2, 0
	v_add_u32_e32 v1, 0x10120, v10
	ds_read_b32 v1, v1
	v_lshlrev_b32_e32 v2, 15, v96
	v_mov_b32_e32 v3, v97
	v_lshl_add_u64 v[2:3], v[2:3], 2, s[68:69]
	v_lshlrev_b64 v[4:5], 20, v[96:97]
	s_waitcnt lgkmcnt(0)
	v_sub_u32_e32 v6, v7, v6
	v_sub_u32_e32 v0, v0, v1
	v_lshlrev_b32_e32 v122, 7, v0
	v_ashrrev_i32_e32 v123, 31, v122
	v_lshl_add_u64 v[0:1], v[122:123], 2, v[2:3]
	v_mov_b32_e32 v56, 0
	s_mov_b32 s2, 0
	s_mov_b32 s27, 0
	v_mov_b32_e32 v57, v56
	v_mov_b32_e32 v58, v56
	v_mov_b32_e32 v59, v56
	v_mov_b32_e32 v48, v56
	v_mov_b32_e32 v49, v56
	v_mov_b32_e32 v50, v56
	v_mov_b32_e32 v51, v56
	v_mov_b32_e32 v60, v56
	v_mov_b32_e32 v61, v56
	v_mov_b32_e32 v62, v56
	v_mov_b32_e32 v63, v56
	v_mov_b32_e32 v52, v56
	v_mov_b32_e32 v53, v56
	v_mov_b32_e32 v54, v56
	v_mov_b32_e32 v55, v56
	v_mov_b32_e32 v40, v56
	v_mov_b32_e32 v41, v56
	v_mov_b32_e32 v42, v56
	v_mov_b32_e32 v43, v56
	v_mov_b32_e32 v32, v56
	v_mov_b32_e32 v33, v56
	v_mov_b32_e32 v34, v56
	v_mov_b32_e32 v35, v56
	v_mov_b32_e32 v44, v56
	v_mov_b32_e32 v45, v56
	v_mov_b32_e32 v46, v56
	v_mov_b32_e32 v47, v56
	v_mov_b32_e32 v36, v56
	v_mov_b32_e32 v37, v56
	v_mov_b32_e32 v38, v56
	v_mov_b32_e32 v39, v56
	v_mov_b32_e32 v24, v56
	v_mov_b32_e32 v25, v56
	v_mov_b32_e32 v26, v56
	v_mov_b32_e32 v27, v56
	v_mov_b32_e32 v16, v56
	v_mov_b32_e32 v17, v56
	v_mov_b32_e32 v18, v56
	v_mov_b32_e32 v19, v56
	v_mov_b32_e32 v28, v56
	v_mov_b32_e32 v29, v56
	v_mov_b32_e32 v30, v56
	v_mov_b32_e32 v31, v56
	v_mov_b32_e32 v20, v56
	v_mov_b32_e32 v21, v56
	v_mov_b32_e32 v22, v56
	v_mov_b32_e32 v23, v56
	s_waitcnt vmcnt(0)
	v_sub_u32_e32 v2, v6, v122
	v_min_i32_e32 v123, 0x80, v2
	v_cmp_lt_i32_e32 vcc, v160, v123
	v_readfirstlane_b32 s98, v123
	s_lshr_b32 s99, s100, 11
	s_cmp_le_u32 s98, 64
	s_cselect_b32 s98, 1, 0
	s_and_b32 s99, s99, s98
	s_nop 1
	v_cndmask_b32_e32 v2, 0, v160, vcc
	v_cmp_lt_i32_e32 vcc, v150, v123
	v_lshlrev_b32_e32 v96, 2, v2
	v_lshl_add_u64 v[2:3], v[0:1], 0, v[96:97]
	v_cndmask_b32_e32 v6, 0, v150, vcc
	v_cmp_lt_i32_e32 vcc, v151, v123
	v_lshlrev_b32_e32 v96, 2, v6
	v_lshl_add_u64 v[6:7], v[0:1], 0, v[96:97]
	v_cndmask_b32_e32 v8, 0, v151, vcc
	v_cmp_lt_i32_e32 vcc, v152, v123
	v_lshlrev_b32_e32 v96, 2, v8
	v_lshl_add_u64 v[8:9], v[0:1], 0, v[96:97]
	v_cndmask_b32_e32 v11, 0, v152, vcc
	v_lshlrev_b32_e32 v96, 2, v11
	global_load_dword v2, v[2:3], off
	v_lshl_add_u64 v[0:1], v[0:1], 0, v[96:97]
	global_load_dword v6, v[6:7], off
	v_add_u32_e32 v96, 0x10000, v10
	global_load_dword v8, v[8:9], off
	v_lshl_add_u64 v[10:11], s[74:75], 0, v[4:5]
	global_load_dword v0, v[0:1], off
	v_lshl_add_u64 v[4:5], s[76:77], 0, v[4:5]
	v_cndmask_b32_e64 v133, v5, v11, s[6:7]
	v_cndmask_b32_e64 v132, v4, v10, s[6:7]
	v_cndmask_b32_e64 v135, v11, v5, s[6:7]
	v_cndmask_b32_e64 v134, v10, v4, s[6:7]
	v_cndmask_b32_e64 v137, v5, v11, s[8:9]
	v_cndmask_b32_e64 v136, v4, v10, s[8:9]
	v_lshl_add_u64 v[4:5], v[132:133], 0, v[112:113]
	v_lshl_add_u64 v[10:11], v[134:135], 0, v[114:115]
	v_lshl_add_u64 v[12:13], v[132:133], 0, v[116:117]
	v_lshl_add_u64 v[14:15], v[136:137], 0, v[118:119]
	v_lshl_add_u64 v[4:5], v[4:5], 0, v[92:93]
	v_lshl_add_u64 v[10:11], v[10:11], 0, v[92:93]
	v_lshl_add_u64 v[12:13], v[12:13], 0, v[92:93]
	v_lshl_add_u64 v[14:15], v[14:15], 0, v[92:93]
	s_add_u32 m0, s100, 0x4000
	s_nop 0
	global_load_lds_dwordx4 v[4:5], off
	s_add_u32 m0, s100, 0x5000
	s_nop 0
	global_load_lds_dwordx4 v[10:11], off
	s_add_u32 m0, s100, 0x6000
	s_nop 0
	global_load_lds_dwordx4 v[12:13], off
	s_add_u32 m0, s100, 0x7000
	s_nop 0
	global_load_lds_dwordx4 v[14:15], off
	v_lshl_add_u64 v[138:139], v[132:133], 0, s[4:5]
	v_lshl_add_u64 v[134:135], v[134:135], 0, v[106:107]
	v_lshl_add_u64 v[176:177], v[136:137], 0, v[110:111]
	v_mov_b32_e32 v10, v56
	v_mov_b32_e32 v11, v56
	v_mov_b32_e32 v12, v56
	v_mov_b32_e32 v13, v56
	v_mov_b32_e32 v14, v56
	v_mov_b32_e32 v15, v56
	v_lshl_add_u64 v[132:133], v[138:139], 0, v[104:105]
	v_lshl_add_u64 v[134:135], v[134:135], 0, s[4:5]
	v_lshl_add_u64 v[136:137], v[138:139], 0, v[108:109]
	v_lshl_add_u64 v[138:139], v[176:177], 0, s[4:5]
	s_waitcnt vmcnt(7)
	v_ashrrev_i32_e32 v3, 31, v2
	v_lshlrev_b64 v[140:141], 11, v[2:3]
	s_waitcnt vmcnt(6)
	v_ashrrev_i32_e32 v7, 31, v6
	v_lshl_add_u64 v[2:3], v[100:101], 0, v[140:141]
	s_waitcnt vmcnt(5)
	v_ashrrev_i32_e32 v9, 31, v8
	v_lshlrev_b64 v[144:145], 11, v[8:9]
	s_waitcnt vmcnt(4)
	v_ashrrev_i32_e32 v1, 31, v0
	v_lshlrev_b64 v[142:143], 11, v[6:7]
	v_lshl_add_u64 v[6:7], v[100:101], 0, v[144:145]
	v_lshlrev_b64 v[146:147], 11, v[0:1]
	v_lshl_add_u64 v[4:5], v[100:101], 0, v[142:143]
	s_add_u32 m0, s100, 0x0
	v_lshl_add_u64 v[90:91], v[2:3], 0, v[94:95]
	global_load_lds_dwordx4 v[90:91], off
	s_add_u32 m0, s100, 0x1000
	v_lshl_add_u64 v[90:91], v[4:5], 0, v[94:95]
	global_load_lds_dwordx4 v[90:91], off
	v_lshl_add_u64 v[0:1], v[100:101], 0, v[146:147]
	s_add_u32 m0, s100, 0x2000
	v_lshl_add_u64 v[90:91], v[6:7], 0, v[94:95]
	global_load_lds_dwordx4 v[90:91], off
	s_add_u32 m0, s100, 0x3000
	v_lshl_add_u64 v[90:91], v[0:1], 0, v[94:95]
	global_load_lds_dwordx4 v[90:91], off
	ds_read_b32 v96, v96
	v_mov_b32_e32 v8, v56
	v_mov_b32_e32 v9, v56
	v_mov_b32_e32 v0, v56
	v_mov_b32_e32 v1, v56
	v_mov_b32_e32 v2, v56
	v_mov_b32_e32 v3, v56
	v_mov_b32_e32 v4, v56
	v_mov_b32_e32 v5, v56
	v_mov_b32_e32 v6, v56
	v_lshl_add_u64 v[140:141], s[10:11], 0, v[140:141]
	v_lshl_add_u64 v[142:143], s[10:11], 0, v[142:143]
	v_lshl_add_u64 v[144:145], s[10:11], 0, v[144:145]
	v_lshl_add_u64 v[146:147], s[10:11], 0, v[146:147]
	v_mov_b32_e32 v7, v56
	s_waitcnt vmcnt(0)
	s_waitcnt lgkmcnt(0)
	s_barrier
	s_branch .LBB0_1278

; template <bool ABF, bool BBF, class RowF, class ColF, class Epi>
; __device__ __forceinline__ void gemm_tile(char* smem, int K, RowF rowptr, ColF colptr, int ldb, Epi epi) {
;     ...
;   for (int k0 = 0; k0 < K; k0 += BK) {
;     if (k0 + BK < K) gload(k0 + BK);
;     const u16* As = As0 + cur * (GEMM_SMEM / 2);
;     const u16* Bs = As + BM * LDT;
;     {
;       bf16x8 af[2][4], bfr[2][4];
; #pragma unroll
;       for (int ks = 0; ks < 2; ks++) {
; #pragma unroll
;         for (int mi = 0; mi < 4; mi++) af[ks][mi] = *(const bf16x8*)&As[(wm * 64 + mi * 16 + l15) * LDT + (((ks * 4 + kg) ^ swz) << 3)];
; #pragma unroll
;         for (int ni = 0; ni < 4; ni++) bfr[ks][ni] = *(const bf16x8*)&Bs[(wn * 64 + ni * 16 + l15) * LDT + (((ks * 4 + kg) ^ swz) << 3)];
;       }
;       __builtin_amdgcn_sched_barrier(0);
; #pragma unroll
;       for (int ks = 0; ks < 2; ks++)
; #pragma unroll
;         for (int mi = 0; mi < 4; mi++)
; #pragma unroll
;           for (int ni = 0; ni < 4; ni++)
;             acc[mi][ni] = __builtin_amdgcn_mfma_f32_16x16x32_bf16(bfr[ks][ni], af[ks][mi], acc[mi][ni], 0, 0, 0);
;       __builtin_amdgcn_sched_barrier(0);
;     }
;     if (k0 + BK < K) sstore(cur ^ 1);
.LBB0_1278:
	s_cmpk_lt_u32 s2, 0x3c0
	s_cselect_b64 s[20:21], -1, 0
	s_cmpk_gt_u32 s2, 0x3bf
	s_cselect_b64 s[18:19], -1, 0
	s_and_b64 vcc, exec, s[18:19]
	s_cbranch_vccnz .LBB0_1280
	s_xor_b32 s101, s27, 1
	s_lshl_b32 s101, s101, 15
	s_add_u32 s101, s101, s100
	s_waitcnt vmcnt(3)
	v_lshl_add_u64 v[64:65], v[140:141], 0, v[92:93]
	s_add_u32 m0, s101, 0x0
	s_nop 0
	global_load_lds_dwordx4 v[64:65], off
	v_lshl_add_u64 v[64:65], v[142:143], 0, v[92:93]
	s_add_u32 m0, s101, 0x1000
	s_nop 0
	global_load_lds_dwordx4 v[64:65], off
	v_lshl_add_u64 v[64:65], v[144:145], 0, v[92:93]
	s_add_u32 m0, s101, 0x2000
	s_nop 0
	global_load_lds_dwordx4 v[64:65], off
	v_lshl_add_u64 v[64:65], v[146:147], 0, v[92:93]
	s_add_u32 m0, s101, 0x3000
	s_nop 0
	global_load_lds_dwordx4 v[64:65], off
	v_lshl_add_u64 v[64:65], v[132:133], 0, v[92:93]
	s_waitcnt vmcnt(6)
	v_lshl_add_u64 v[68:69], v[134:135], 0, v[92:93]
	s_waitcnt vmcnt(5)
	v_lshl_add_u64 v[72:73], v[136:137], 0, v[92:93]
	s_waitcnt vmcnt(4)
	v_lshl_add_u64 v[80:81], v[138:139], 0, v[92:93]
	s_add_u32 m0, s101, 0x4000
	s_nop 0
	global_load_lds_dwordx4 v[64:65], off
	s_nop 0
	s_add_u32 m0, s101, 0x5000
	s_nop 0
	global_load_lds_dwordx4 v[68:69], off
	s_nop 0
	s_add_u32 m0, s101, 0x6000
	s_nop 0
	global_load_lds_dwordx4 v[72:73], off
	s_nop 0
	s_add_u32 m0, s101, 0x7000
	s_nop 0
	global_load_lds_dwordx4 v[80:81], off
.LBB0_1280:
	s_cmp_lg_u32 s99, 0
	s_cbranch_scc1 .Le1_skipc
	s_lshl_b32 s28, s27, 15
	s_add_i32 s28, s28, 0
	v_lshlrev_b32_e32 v176, 1, v163
	v_add_u32_e32 v192, s28, v176
	v_lshlrev_b32_e32 v208, 1, v164
	v_lshl_add_u32 v224, v165, 1, s28
	v_add_u32_e32 v177, v192, v208
	v_add3_u32 v188, s28, v208, v176
	v_add_u32_e32 v204, v192, v175
	v_add_u32_e32 v220, v224, v208
	v_add_u32_e32 v236, v224, v175
	ds_read_b128 v[176:179], v177
	ds_read_b128 v[180:183], v188 offset:2048
	ds_read_b128 v[184:187], v188 offset:4096
	ds_read_b128 v[188:191], v188 offset:6144
	ds_read_b128 v[192:195], v204 offset:16384
	ds_read_b128 v[196:199], v204 offset:18432
	ds_read_b128 v[200:203], v204 offset:20480
	ds_read_b128 v[204:207], v204 offset:22528
	ds_read_b128 v[208:211], v220
	ds_read_b128 v[212:215], v220 offset:2048
	ds_read_b128 v[216:219], v220 offset:4096
	ds_read_b128 v[220:223], v220 offset:6144
	ds_read_b128 v[224:227], v236 offset:16384
	ds_read_b128 v[228:231], v236 offset:18432
	ds_read_b128 v[232:235], v236 offset:20480
	ds_read_b128 v[236:239], v236 offset:22528
	s_waitcnt lgkmcnt(11)
	v_mfma_f32_16x16x32_bf16 v[56:59], v[192:195], v[176:179], v[56:59]
	s_waitcnt lgkmcnt(10)
	v_mfma_f32_16x16x32_bf16 v[48:51], v[196:199], v[176:179], v[48:51]
	s_waitcnt lgkmcnt(9)
	v_mfma_f32_16x16x32_bf16 v[60:63], v[200:203], v[176:179], v[60:63]
	s_waitcnt lgkmcnt(8)
	v_mfma_f32_16x16x32_bf16 v[52:55], v[204:207], v[176:179], v[52:55]
	v_mfma_f32_16x16x32_bf16 v[40:43], v[192:195], v[180:183], v[40:43]
	v_mfma_f32_16x16x32_bf16 v[32:35], v[196:199], v[180:183], v[32:35]
	v_mfma_f32_16x16x32_bf16 v[44:47], v[200:203], v[180:183], v[44:47]
	v_mfma_f32_16x16x32_bf16 v[36:39], v[204:207], v[180:183], v[36:39]
	v_mfma_f32_16x16x32_bf16 v[24:27], v[192:195], v[184:187], v[24:27]
	v_mfma_f32_16x16x32_bf16 v[16:19], v[196:199], v[184:187], v[16:19]
	v_mfma_f32_16x16x32_bf16 v[28:31], v[200:203], v[184:187], v[28:31]
	v_mfma_f32_16x16x32_bf16 v[20:23], v[204:207], v[184:187], v[20:23]
	v_mfma_f32_16x16x32_bf16 v[8:11], v[192:195], v[188:191], v[8:11]
	v_mfma_f32_16x16x32_bf16 v[0:3], v[196:199], v[188:191], v[0:3]
	v_mfma_f32_16x16x32_bf16 v[12:15], v[200:203], v[188:191], v[12:15]
	v_mfma_f32_16x16x32_bf16 v[4:7], v[204:207], v[188:191], v[4:7]
	s_waitcnt lgkmcnt(3)
	v_mfma_f32_16x16x32_bf16 v[56:59], v[224:227], v[208:211], v[56:59]
	s_waitcnt lgkmcnt(2)
	v_mfma_f32_16x16x32_bf16 v[48:51], v[228:231], v[208:211], v[48:51]
	s_waitcnt lgkmcnt(1)
	v_mfma_f32_16x16x32_bf16 v[60:63], v[232:235], v[208:211], v[60:63]
	s_waitcnt lgkmcnt(0)
	v_mfma_f32_16x16x32_bf16 v[52:55], v[236:239], v[208:211], v[52:55]
	v_mfma_f32_16x16x32_bf16 v[40:43], v[224:227], v[212:215], v[40:43]
	v_mfma_f32_16x16x32_bf16 v[32:35], v[228:231], v[212:215], v[32:35]
	v_mfma_f32_16x16x32_bf16 v[44:47], v[232:235], v[212:215], v[44:47]
	v_mfma_f32_16x16x32_bf16 v[36:39], v[236:239], v[212:215], v[36:39]
	v_mfma_f32_16x16x32_bf16 v[24:27], v[224:227], v[216:219], v[24:27]
	v_mfma_f32_16x16x32_bf16 v[16:19], v[228:231], v[216:219], v[16:19]
	v_mfma_f32_16x16x32_bf16 v[28:31], v[232:235], v[216:219], v[28:31]
	v_mfma_f32_16x16x32_bf16 v[20:23], v[236:239], v[216:219], v[20:23]
	v_mfma_f32_16x16x32_bf16 v[8:11], v[224:227], v[220:223], v[8:11]
	v_mfma_f32_16x16x32_bf16 v[0:3], v[228:231], v[220:223], v[0:3]
	v_mfma_f32_16x16x32_bf16 v[12:15], v[232:235], v[220:223], v[12:15]
	v_mfma_f32_16x16x32_bf16 v[4:7], v[236:239], v[220:223], v[4:7]

; template <bool ABF, bool BBF, class RowF, class ColF, class Epi>
; __device__ __forceinline__ void gemm_tile(char* smem, int K, RowF rowptr, ColF colptr, int ldb, Epi epi) {
;     ...
;   auto gload = [&](int k0) {
; #pragma unroll
;     for (int i = 0; i < NA; i++) ra[i] = *(const u32x4*)(ap[i] + (size_t)k0 * (ABF ? 2 : 4));
;     if (BBF) {
; #pragma unroll
;       for (int i = 0; i < 4; i++) rbb[BBF ? i : 0] = *(const u32x4*)(bq[i] + (size_t)k0 * 2);
;     } else {
;       const float* b = bp + (size_t)k0 * ldb;
; #pragma unroll
;       for (int j = 0; j < 32; j++) rb[BBF ? 0 : j] = b[(size_t)j * ldb];
; __device__ void phaseE2(const Params& p, char* smem) {
;     ...
;   xcd_queue_run(p.bar + QW_BASE + 1536, s_rb[NEXP], smem + 2 * GEMM_SMEM + 800, [&](int j, int q) {
;     const int rbg = q, nt = j;
;     int e = 0;
;     while (s_rb[e + 1] <= rbg) e++;
;     const int rb = rbg - s_rb[e];
;     const int cnt = p.cnt[e];
;     const int rows = min(128, cnt - rb * 128);
;     const int slot0 = s_off[e] + rb * 128;
;     const int n0 = nt * 128;
;     const float* wd = p.w_down + (size_t)e * DEXP * DM;
;     const float* lg = p.list_gate + e * CAP + rb * 128;
;     auto rowf = [&](int r) { int rr = r < rows ? r : 0; return (const void*)(p.H + (size_t)(slot0 + rr) * DEXP); };
;     auto colf = [&](int c) { return (const void*)(wd + n0 + c); };
.LBB0_1355:
	s_or_b64 exec, exec, s[16:17]
	s_cmp_lg_u32 s33, -1
	s_cselect_b32 s2, s33, 0
	s_cselect_b32 s16, s1, 0
	v_mov_b32_e32 v0, s2
	v_mov_b32_e32 v1, s16
	s_waitcnt lgkmcnt(0)
	s_barrier
	flat_load_dword v2, v[0:1] sc0 sc1
	s_waitcnt vmcnt(0)
	s_mov_b64 s[18:19], -1
	s_waitcnt lgkmcnt(0)
	v_cmp_lt_i32_e32 vcc, v2, v108
	s_and_saveexec_b64 s[16:17], vcc
	s_cbranch_execz .LBB0_1350
	s_mov_b64 s[18:19], 0
	v_mbcnt_lo_u32_b32 v3, -1, 0
	v_mbcnt_hi_u32_b32 v3, -1, v3
	v_lshl_add_u32 v3, v3, 2, s24
	ds_read_b32 v3, v3
	s_waitcnt lgkmcnt(0)
	v_cmp_le_i32_e32 vcc, v3, v2
	s_bcnt1_i32_b64 s2, vcc
	v_mov_b32_e32 v80, s2
	s_lshl_b32 s20, s2, 21
	s_mov_b32 s21, 0
	v_lshl_add_u64 v[96:97], v[90:91], 0, s[20:21]
	s_or_b64 exec, exec, s[18:19]
	v_mul_u32_u24_e32 v0, 0x20100, v80
	v_mov_b32_e32 v1, 0
	v_lshl_add_u64 v[0:1], v[0:1], 0, s[62:63]
	global_load_dword v3, v[0:1], off
	v_lshl_add_u32 v4, v80, 2, 0
	v_lshlrev_b64 v[0:1], 21, v[80:81]
	v_add_u32_e32 v5, 0x10120, v4
	v_add_u32_e32 v4, 0x10000, v4
	v_lshl_add_u64 v[0:1], v[92:93], 0, v[0:1]
	ds_read_b32 v22, v5
	ds_read_b32 v23, v4
	v_add_co_u32_e32 v4, vcc, s26, v0
	v_mov_b32_e32 v64, 0
	s_nop 0
	v_addc_co_u32_e32 v5, vcc, 0, v1, vcc
	v_add_co_u32_e32 v6, vcc, s27, v0
	s_waitcnt lgkmcnt(1)
	v_sub_u32_e32 v2, v2, v22
	v_addc_co_u32_e32 v7, vcc, 0, v1, vcc
	v_add_co_u32_e32 v8, vcc, s28, v0
	v_lshlrev_b32_e32 v98, 7, v2
	s_nop 0
	v_addc_co_u32_e32 v9, vcc, 0, v1, vcc
	v_add_co_u32_e32 v10, vcc, s29, v0
	s_waitcnt lgkmcnt(0)
	v_add_u32_e32 v117, v23, v98
	v_addc_co_u32_e32 v11, vcc, 0, v1, vcc
	v_add_co_u32_e32 v12, vcc, s30, v0
	s_mov_b32 s2, 0
	s_nop 0
	v_addc_co_u32_e32 v13, vcc, 0, v1, vcc
	v_add_co_u32_e32 v14, vcc, s31, v0
	s_mov_b32 s47, 0
	s_nop 0
	v_addc_co_u32_e32 v15, vcc, 0, v1, vcc
	v_add_co_u32_e32 v16, vcc, s36, v0
	v_mov_b32_e32 v65, v64
	s_nop 0
	v_addc_co_u32_e32 v17, vcc, 0, v1, vcc
	v_add_co_u32_e32 v18, vcc, s25, v0
	global_load_dword v141, v[0:1], off
	global_load_dword v99, v[4:5], off offset:-4096
	global_load_dword v119, v[4:5], off
	global_load_dword v120, v[6:7], off offset:-4096
	global_load_dword v121, v[6:7], off
	global_load_dword v122, v[8:9], off offset:-4096
	global_load_dword v123, v[8:9], off
	global_load_dword v128, v[10:11], off offset:-4096
	global_load_dword v130, v[10:11], off
	global_load_dword v132, v[12:13], off offset:-4096
	global_load_dword v133, v[12:13], off
	global_load_dword v134, v[14:15], off offset:-4096
	global_load_dword v135, v[14:15], off
	global_load_dword v136, v[16:17], off offset:-4096
	global_load_dword v137, v[16:17], off
	v_addc_co_u32_e32 v19, vcc, 0, v1, vcc
	v_add_co_u32_e32 v20, vcc, s37, v0
	v_mov_b32_e32 v66, v64
	s_nop 0
	v_addc_co_u32_e32 v21, vcc, 0, v1, vcc
	v_mov_b32_e32 v67, v64
	v_mov_b32_e32 v76, v64
	v_mov_b32_e32 v77, v64
	v_mov_b32_e32 v78, v64
	v_mov_b32_e32 v79, v64
	v_mov_b32_e32 v72, v64
	v_mov_b32_e32 v73, v64
	v_mov_b32_e32 v74, v64
	v_mov_b32_e32 v75, v64
	v_mov_b32_e32 v68, v64
	v_mov_b32_e32 v69, v64
	v_mov_b32_e32 v70, v64
	v_mov_b32_e32 v71, v64
	v_mov_b32_e32 v60, v64
	v_mov_b32_e32 v61, v64
	v_mov_b32_e32 v62, v64
	v_mov_b32_e32 v63, v64
	v_mov_b32_e32 v56, v64
	v_mov_b32_e32 v57, v64
	v_mov_b32_e32 v58, v64
	v_mov_b32_e32 v59, v64
	v_mov_b32_e32 v52, v64
	v_mov_b32_e32 v53, v64
	v_mov_b32_e32 v54, v64
	v_mov_b32_e32 v55, v64
	v_mov_b32_e32 v48, v64
	v_mov_b32_e32 v49, v64
	v_mov_b32_e32 v50, v64
	s_waitcnt vmcnt(15)
; template <bool ABF, bool BBF, class RowF, class ColF, class Epi>
; __device__ __forceinline__ void gemm_tile(char* smem, int K, RowF rowptr, ColF colptr, int ldb, Epi epi) {
;     ...
;   auto gload = [&](int k0) {
; #pragma unroll
;     for (int i = 0; i < NA; i++) ra[i] = *(const u32x4*)(ap[i] + (size_t)k0 * (ABF ? 2 : 4));
;     if (BBF) {
; #pragma unroll
;       for (int i = 0; i < 4; i++) rbb[BBF ? i : 0] = *(const u32x4*)(bq[i] + (size_t)k0 * 2);
;     } else {
;       const float* b = bp + (size_t)k0 * ldb;
; #pragma unroll
;       for (int j = 0; j < 32; j++) rb[BBF ? 0 : j] = b[(size_t)j * ldb];
;     }
;   };
;   auto sstore = [&](int buf) {
;     u16* As = As0 + buf * (GEMM_SMEM / 2);
;     u16* Bs = As + BM * LDT;
; #pragma unroll
;     for (int i = 0; i < NA; i++) {
;       if (ABF) {
;         { const int row = ar0 + ARS * i; *(u32x4*)&As[row * LDT + (((ac >> 3) ^ ((row >> 1) & 7)) << 3)] = ra[i]; }
;       } else {
;         u32x2 v;
;         v[0] = pack2(__uint_as_float(ra[i][0]), __uint_as_float(ra[i][1]));
;         v[1] = pack2(__uint_as_float(ra[i][2]), __uint_as_float(ra[i][3]));
;         { const int row = ar0 + ARS * i; *(u32x2*)&As[row * LDT + (((ac >> 3) ^ ((row >> 1) & 7)) << 3) + (ac & 4)] = v; }
;       }
;     }
;     if (BBF) {
; #pragma unroll
;       for (int i = 0; i < 4; i++) { const int row = br0 + 32 * i; *(u32x4*)&Bs[row * LDT + (((bcc >> 3) ^ ((row >> 1) & 7)) << 3)] = rbb[BBF ? i : 0]; }
;     } else {
; #pragma unroll
;       for (int j = 0; j < 4; j++) {
;         u32x4 v;
;         v[0] = pack2(rb[BBF ? 0 : 8 * j + 0], rb[BBF ? 0 : 8 * j + 1]);
;         v[1] = pack2(rb[BBF ? 0 : 8 * j + 2], rb[BBF ? 0 : 8 * j + 3]);
;         v[2] = pack2(rb[BBF ? 0 : 8 * j + 4], rb[BBF ? 0 : 8 * j + 5]);
;         v[3] = pack2(rb[BBF ? 0 : 8 * j + 6], rb[BBF ? 0 : 8 * j + 7]);
;         *(u32x4*)&Bs[bc * LDT + (((kh * 4 + j) ^ ((bc >> 1) & 7)) << 3)] = v;
;       }
;     }
;   };
;   gload(0);
; __device__ void phaseE2(const Params& p, char* smem) {
;     ...
;     const int cnt = p.cnt[e];
;     const int rows = min(128, cnt - rb * 128);
;     const int slot0 = s_off[e] + rb * 128;
;     const int n0 = nt * 128;
;     const float* wd = p.w_down + (size_t)e * DEXP * DM;
;     const float* lg = p.list_gate + e * CAP + rb * 128;
;     auto rowf = [&](int r) { int rr = r < rows ? r : 0; return (const void*)(p.H + (size_t)(slot0 + rr) * DEXP); };
	v_sub_u32_e32 v2, v3, v98
	v_min_i32_e32 v118, 0x80, v2
	v_cmp_lt_i32_e32 vcc, v160, v118
	v_mov_b32_e32 v51, v64
	v_mov_b32_e32 v28, v64
	v_cndmask_b32_e32 v2, 0, v160, vcc
	v_cmp_lt_i32_e32 vcc, v150, v118
	v_add_u32_e32 v2, v2, v117
	v_mov_b32_e32 v29, v64
	v_cndmask_b32_e32 v3, 0, v150, vcc
	v_cmp_lt_i32_e32 vcc, v151, v118
	v_add_u32_e32 v4, v3, v117
	v_ashrrev_i32_e32 v3, 31, v2
	v_cndmask_b32_e32 v5, 0, v151, vcc
	v_cmp_lt_i32_e32 vcc, v152, v118
	v_add_u32_e32 v6, v5, v117
	v_ashrrev_i32_e32 v5, 31, v4
	v_cndmask_b32_e32 v7, 0, v152, vcc
	v_add_co_u32_e32 v10, vcc, s38, v0
	v_add_u32_e32 v8, v7, v117
	s_nop 0
	v_addc_co_u32_e32 v11, vcc, 0, v1, vcc
	v_add_co_u32_e32 v12, vcc, s39, v0
	v_ashrrev_i32_e32 v7, 31, v6
	s_nop 0
	v_addc_co_u32_e32 v13, vcc, 0, v1, vcc
	global_load_dword v138, v[18:19], off offset:-4096
	global_load_dword v139, v[18:19], off
	global_load_dword v140, v[20:21], off offset:-4096
	global_load_dword v142, v[20:21], off
	global_load_dword v143, v[10:11], off offset:-4096
	global_load_dword v144, v[10:11], off
	global_load_dword v145, v[12:13], off offset:-4096
	global_load_dword v146, v[12:13], off
	v_add_co_u32_e32 v10, vcc, s40, v0
	v_lshlrev_b64 v[16:17], 10, v[2:3]
	s_nop 0
	v_addc_co_u32_e32 v11, vcc, 0, v1, vcc
	v_add_co_u32_e32 v12, vcc, s41, v0
	v_ashrrev_i32_e32 v9, 31, v8
	s_nop 0
	v_addc_co_u32_e32 v13, vcc, 0, v1, vcc
	v_add_co_u32_e32 v14, vcc, s42, v0
	v_lshlrev_b64 v[22:23], 10, v[4:5]
	s_nop 0
	v_addc_co_u32_e32 v15, vcc, 0, v1, vcc
	v_add_co_u32_e32 v18, vcc, s43, v0
	v_lshlrev_b64 v[24:25], 10, v[6:7]
	s_nop 0
	v_addc_co_u32_e32 v19, vcc, 0, v1, vcc
	v_add_co_u32_e32 v0, vcc, s44, v0
	v_lshl_add_u64 v[2:3], v[86:87], 0, v[16:17]
	s_nop 0
	v_addc_co_u32_e32 v1, vcc, 0, v1, vcc
	global_load_dword v147, v[10:11], off offset:-4096
	global_load_dword v153, v[10:11], off
	global_load_dword v154, v[12:13], off offset:-4096
	global_load_dword v155, v[12:13], off
	global_load_dword v156, v[14:15], off offset:-4096
	global_load_dword v157, v[14:15], off
	global_load_dword v158, v[18:19], off offset:-4096
	global_load_dword v159, v[18:19], off
	global_load_dword v170, v[0:1], off
	v_lshlrev_b64 v[18:19], 10, v[8:9]
	v_lshl_add_u64 v[4:5], v[86:87], 0, v[22:23]
	v_lshl_add_u64 v[6:7], v[86:87], 0, v[24:25]
	v_lshl_add_u64 v[0:1], v[86:87], 0, v[18:19]
	v_lshrrev_b32_e32 v46, 2, v149
	v_lshrrev_b32_e32 v35, 4, v46
	v_xor_b32_e32 v35, v35, v46
	v_and_b32_e32 v35, 7, v35
	v_lshlrev_b32_e32 v34, 4, v35
	v_mov_b32_e32 v35, 0
	v_sub_u32_e32 v38, v34, v124
	v_lshrrev_b32_e32 v46, 6, v46
	v_ashrrev_i32_e32 v39, 31, v38
	v_readfirstlane_b32 s100, v46
	s_lshl_b32 s100, s100, 10
	v_readfirstlane_b32 s98, v118
	s_lshr_b32 s99, s100, 11
	s_cmp_le_u32 s98, 64
	s_cselect_b32 s98, 1, 0
	s_and_b32 s99, s99, s98
	s_add_u32 m0, s100, 0x0
	v_lshl_add_u64 v[42:43], v[2:3], 0, v[38:39]
	global_load_lds_dwordx4 v[42:43], off
	s_add_u32 m0, s100, 0x1000
	v_lshl_add_u64 v[42:43], v[4:5], 0, v[38:39]
	global_load_lds_dwordx4 v[42:43], off
	s_add_u32 m0, s100, 0x2000
	v_lshl_add_u64 v[42:43], v[6:7], 0, v[38:39]
	global_load_lds_dwordx4 v[42:43], off
	s_add_u32 m0, s100, 0x3000
	v_lshl_add_u64 v[42:43], v[0:1], 0, v[38:39]
	global_load_lds_dwordx4 v[42:43], off
	s_waitcnt vmcnt(34)
	v_cvt_pk_bf16_f32 v0, v141, v99
	s_waitcnt vmcnt(32)
	v_cvt_pk_bf16_f32 v1, v119, v120
	s_waitcnt vmcnt(30)
	v_cvt_pk_bf16_f32 v2, v121, v122
	s_waitcnt vmcnt(28)
	v_cvt_pk_bf16_f32 v3, v123, v128
	s_waitcnt vmcnt(26)
	v_cvt_pk_bf16_f32 v4, v130, v132
	s_waitcnt vmcnt(24)
	v_cvt_pk_bf16_f32 v5, v133, v134
	s_waitcnt vmcnt(22)
	v_cvt_pk_bf16_f32 v6, v135, v136
	v_lshl_add_u64 v[100:101], s[8:9], 0, v[16:17]
	v_lshl_add_u64 v[102:103], s[8:9], 0, v[22:23]
	v_lshl_add_u64 v[104:105], s[8:9], 0, v[24:25]
	v_lshl_add_u64 v[106:107], s[8:9], 0, v[18:19]
	v_mov_b32_e32 v30, v64
	v_mov_b32_e32 v31, v64
	v_mov_b32_e32 v24, v64
	v_mov_b32_e32 v25, v64
	v_mov_b32_e32 v26, v64
	v_mov_b32_e32 v27, v64
	v_mov_b32_e32 v20, v64
	v_mov_b32_e32 v21, v64
	v_mov_b32_e32 v22, v64
	v_mov_b32_e32 v23, v64
	v_mov_b32_e32 v16, v64
	v_mov_b32_e32 v17, v64
	v_mov_b32_e32 v18, v64
	v_mov_b32_e32 v19, v64
	s_waitcnt vmcnt(20)
	v_cvt_pk_bf16_f32 v7, v137, v138
	s_waitcnt vmcnt(18)
	v_cvt_pk_bf16_f32 v8, v139, v140
	s_waitcnt vmcnt(16)
	v_cvt_pk_bf16_f32 v9, v142, v143
	s_waitcnt vmcnt(14)
	v_cvt_pk_bf16_f32 v10, v144, v145
	s_waitcnt vmcnt(12)
	v_cvt_pk_bf16_f32 v11, v146, v147
	s_waitcnt vmcnt(10)
	v_cvt_pk_bf16_f32 v12, v153, v154
	s_waitcnt vmcnt(8)
	v_cvt_pk_bf16_f32 v13, v155, v156
	s_waitcnt vmcnt(6)
	v_cvt_pk_bf16_f32 v14, v157, v158
	s_waitcnt vmcnt(4)
	v_cvt_pk_bf16_f32 v15, v159, v170
	s_waitcnt vmcnt(3)
	s_waitcnt vmcnt(2)
	s_waitcnt vmcnt(1)
	s_waitcnt vmcnt(0)
	ds_write_b128 v113, v[0:3] offset:16384
	ds_write_b128 v114, v[4:7] offset:16384
	ds_write_b128 v115, v[8:11] offset:16384
	ds_write_b128 v116, v[12:15] offset:16384
	v_mov_b32_e32 v12, v64
	v_mov_b32_e32 v13, v64
	v_mov_b32_e32 v14, v64
	v_mov_b32_e32 v15, v64
	v_mov_b32_e32 v8, v64
	v_mov_b32_e32 v9, v64
	v_mov_b32_e32 v10, v64
	v_mov_b32_e32 v11, v64
	v_mov_b32_e32 v4, v64
	v_mov_b32_e32 v5, v64
	v_mov_b32_e32 v6, v64
	v_mov_b32_e32 v7, v64
	v_mov_b32_e32 v0, v64
	v_mov_b32_e32 v1, v64
	v_mov_b32_e32 v2, v64
	v_mov_b32_e32 v3, v64
	s_waitcnt lgkmcnt(0)
	s_barrier
	s_branch .LBB0_1360

; template <bool ABF, bool BBF, class RowF, class ColF, class Epi>
; __device__ __forceinline__ void gemm_tile(char* smem, int K, RowF rowptr, ColF colptr, int ldb, Epi epi) {
;     ...
; #pragma unroll
;       for (int j = 0; j < 4; j++) {
;         u32x4 v;
;         v[0] = pack2(rb[BBF ? 0 : 8 * j + 0], rb[BBF ? 0 : 8 * j + 1]);
;         v[1] = pack2(rb[BBF ? 0 : 8 * j + 2], rb[BBF ? 0 : 8 * j + 3]);
;         v[2] = pack2(rb[BBF ? 0 : 8 * j + 4], rb[BBF ? 0 : 8 * j + 5]);
;         v[3] = pack2(rb[BBF ? 0 : 8 * j + 6], rb[BBF ? 0 : 8 * j + 7]);
;         *(u32x4*)&Bs[bc * LDT + (((kh * 4 + j) ^ ((bc >> 1) & 7)) << 3)] = v;
;       }
;     ...
;   for (int k0 = 0; k0 < K; k0 += BK) {
;     if (k0 + BK < K) gload(k0 + BK);
;     const u16* As = As0 + cur * (GEMM_SMEM / 2);
;     const u16* Bs = As + BM * LDT;
;     {
;       bf16x8 af[2][4], bfr[2][4];
; #pragma unroll
;       for (int ks = 0; ks < 2; ks++) {
; #pragma unroll
;         for (int mi = 0; mi < 4; mi++) af[ks][mi] = *(const bf16x8*)&As[(wm * 64 + mi * 16 + l15) * LDT + (((ks * 4 + kg) ^ swz) << 3)];
; #pragma unroll
;         for (int ni = 0; ni < 4; ni++) bfr[ks][ni] = *(const bf16x8*)&Bs[(wn * 64 + ni * 16 + l15) * LDT + (((ks * 4 + kg) ^ swz) << 3)];
;       }
;       __builtin_amdgcn_sched_barrier(0);
; #pragma unroll
;       for (int ks = 0; ks < 2; ks++)
; #pragma unroll
;         for (int mi = 0; mi < 4; mi++)
; #pragma unroll
;           for (int ni = 0; ni < 4; ni++)
;             acc[mi][ni] = __builtin_amdgcn_mfma_f32_16x16x32_bf16(bfr[ks][ni], af[ks][mi], acc[mi][ni], 0, 0, 0);
;       __builtin_amdgcn_sched_barrier(0);
;     }
;     if (k0 + BK < K) sstore(cur ^ 1);
;     __syncthreads();
.LBB0_1362:
	s_cmp_lg_u32 s99, 0
	s_cbranch_scc1 .Le2_skipc
	s_lshl_b32 s48, s47, 15
	s_add_i32 s48, s48, 0
	v_lshlrev_b32_e32 v220, 1, v162
	v_lshlrev_b32_e32 v171, 1, v163
	v_lshlrev_b32_e32 v204, 1, v164
	v_add_u32_e32 v221, s48, v220
	v_add3_u32 v172, s48, v171, v204
	v_add3_u32 v184, s48, v204, v171
	v_add_u32_e32 v171, v221, v171
	ds_read_b128 v[172:175], v172
	ds_read_b128 v[176:179], v184 offset:2048
	ds_read_b128 v[180:183], v184 offset:4096
	ds_read_b128 v[184:187], v184 offset:6144
	ds_read_b128 v[188:191], v171 offset:16384
	ds_read_b128 v[192:195], v171 offset:18432
	ds_read_b128 v[196:199], v171 offset:20480
	ds_read_b128 v[200:203], v171 offset:22528
	v_lshlrev_b32_e32 v171, 1, v165
	v_add_u32_e32 v222, s48, v171
	v_add_u32_e32 v216, v222, v204
	v_add_u32_e32 v220, v222, v220
	ds_read_b128 v[204:207], v216
	ds_read_b128 v[208:211], v216 offset:2048
	ds_read_b128 v[212:215], v216 offset:4096
	ds_read_b128 v[216:219], v216 offset:6144
	v_add_u32_e32 v171, v221, v171
	ds_read_b128 v[220:223], v220 offset:16384
	ds_read_b128 v[224:227], v171 offset:18432
	ds_read_b128 v[228:231], v171 offset:20480
	ds_read_b128 v[232:235], v171 offset:22528
	s_waitcnt lgkmcnt(11)
	v_mfma_f32_16x16x32_bf16 v[64:67], v[188:191], v[172:175], v[64:67]
	s_waitcnt lgkmcnt(10)
	v_mfma_f32_16x16x32_bf16 v[76:79], v[192:195], v[172:175], v[76:79]
	s_waitcnt lgkmcnt(9)
	v_mfma_f32_16x16x32_bf16 v[72:75], v[196:199], v[172:175], v[72:75]
	s_waitcnt lgkmcnt(8)
	v_mfma_f32_16x16x32_bf16 v[68:71], v[200:203], v[172:175], v[68:71]
	v_mfma_f32_16x16x32_bf16 v[60:63], v[188:191], v[176:179], v[60:63]
	v_mfma_f32_16x16x32_bf16 v[56:59], v[192:195], v[176:179], v[56:59]
	v_mfma_f32_16x16x32_bf16 v[52:55], v[196:199], v[176:179], v[52:55]
	v_mfma_f32_16x16x32_bf16 v[48:51], v[200:203], v[176:179], v[48:51]
	v_mfma_f32_16x16x32_bf16 v[28:31], v[188:191], v[180:183], v[28:31]
	v_mfma_f32_16x16x32_bf16 v[24:27], v[192:195], v[180:183], v[24:27]
	v_mfma_f32_16x16x32_bf16 v[20:23], v[196:199], v[180:183], v[20:23]
	v_mfma_f32_16x16x32_bf16 v[16:19], v[200:203], v[180:183], v[16:19]
	v_mfma_f32_16x16x32_bf16 v[12:15], v[188:191], v[184:187], v[12:15]
	v_mfma_f32_16x16x32_bf16 v[8:11], v[192:195], v[184:187], v[8:11]
	v_mfma_f32_16x16x32_bf16 v[4:7], v[196:199], v[184:187], v[4:7]
	v_mfma_f32_16x16x32_bf16 v[0:3], v[200:203], v[184:187], v[0:3]
	s_waitcnt lgkmcnt(3)
	v_mfma_f32_16x16x32_bf16 v[64:67], v[220:223], v[204:207], v[64:67]
	s_waitcnt lgkmcnt(2)
	v_mfma_f32_16x16x32_bf16 v[76:79], v[224:227], v[204:207], v[76:79]
	s_waitcnt lgkmcnt(1)
	v_mfma_f32_16x16x32_bf16 v[72:75], v[228:231], v[204:207], v[72:75]
	s_waitcnt lgkmcnt(0)
	v_mfma_f32_16x16x32_bf16 v[68:71], v[232:235], v[204:207], v[68:71]
	v_mfma_f32_16x16x32_bf16 v[60:63], v[220:223], v[208:211], v[60:63]
	v_mfma_f32_16x16x32_bf16 v[56:59], v[224:227], v[208:211], v[56:59]
	v_mfma_f32_16x16x32_bf16 v[52:55], v[228:231], v[208:211], v[52:55]
	v_mfma_f32_16x16x32_bf16 v[48:51], v[232:235], v[208:211], v[48:51]
	v_mfma_f32_16x16x32_bf16 v[28:31], v[220:223], v[212:215], v[28:31]
	v_mfma_f32_16x16x32_bf16 v[24:27], v[224:227], v[212:215], v[24:27]
	v_mfma_f32_16x16x32_bf16 v[20:23], v[228:231], v[212:215], v[20:23]
	v_mfma_f32_16x16x32_bf16 v[16:19], v[232:235], v[212:215], v[16:19]
	v_mfma_f32_16x16x32_bf16 v[12:15], v[220:223], v[216:219], v[12:15]
	v_mfma_f32_16x16x32_bf16 v[8:11], v[224:227], v[216:219], v[8:11]
	v_mfma_f32_16x16x32_bf16 v[4:7], v[228:231], v[216:219], v[4:7]
	v_mfma_f32_16x16x32_bf16 v[0:3], v[232:235], v[216:219], v[0:3]
.Le2_skipc:
	s_andn2_b64 vcc, exec, s[20:21]
	s_cbranch_vccnz .LBB0_1359
	s_lshl_b32 s20, s47, 14
	s_xor_b32 s20, s20, 0x4000
	s_lshl_b32 s20, s20, 1
	s_add_i32 s20, s20, 0
	v_lshl_add_u32 v171, v161, 1, s20
	s_waitcnt vmcnt(7)
	v_cvt_pk_bf16_f32 v172, v141, v99
	v_cvt_pk_bf16_f32 v173, v119, v120
	v_cvt_pk_bf16_f32 v174, v121, v122
	v_cvt_pk_bf16_f32 v175, v123, v128
	v_lshl_add_u32 v171, v109, 1, s20
	ds_write_b128 v171, v[172:175] offset:16384
	v_cvt_pk_bf16_f32 v172, v130, v132
	v_cvt_pk_bf16_f32 v173, v133, v134
	v_cvt_pk_bf16_f32 v174, v135, v136
	v_cvt_pk_bf16_f32 v175, v137, v138
	v_lshl_add_u32 v171, v110, 1, s20
	ds_write_b128 v171, v[172:175] offset:16384
	v_cvt_pk_bf16_f32 v172, v139, v140
	v_cvt_pk_bf16_f32 v173, v142, v143
	v_cvt_pk_bf16_f32 v174, v144, v145
	v_cvt_pk_bf16_f32 v175, v146, v147
	v_lshl_add_u32 v171, v111, 1, s20
	ds_write_b128 v171, v[172:175] offset:16384
	s_waitcnt vmcnt(6)
	v_cvt_pk_bf16_f32 v172, v153, v154
	s_waitcnt vmcnt(4)
	v_cvt_pk_bf16_f32 v173, v155, v156
	s_waitcnt vmcnt(2)
	v_cvt_pk_bf16_f32 v174, v157, v158
	s_waitcnt vmcnt(0)
	v_cvt_pk_bf16_f32 v175, v159, v170
	v_lshl_add_u32 v171, v112, 1, s20
	ds_write_b128 v171, v[172:175] offset:16384
	s_branch .LBB0_1359
